# v061 + RG-LRU Y-store and mLSTM h-store blocks: LDS reads issued together instead of read-wait-store x3/x4
# baseline (speedup 1.0000x reference)
; #define LAS __attribute__((address_space(3)))
; DI int opq(int x) { asm volatile("" : "+v"(x)); return x; }
; DI bf16x8 join4(const s16x4& lo, const s16x4& hi) { return __builtin_shufflevector(lo, hi, 0, 1, 2, 3, 4, 5, 6, 7); }
; #define MFMA32(a, b, c) __builtin_amdgcn_mfma_f32_32x32x16_bf16((a), (b), (c), 0, 0, 0)
; DI void phase_mlstm(const Params& p, unsigned char* shm, const int vb) {
;     ...
;             {
;                 const int lane = opq(threadIdx.x) & 63, l32 = lane & 31, hh = lane >> 5;
;                 const int qb = QI + l32 * RS + 8 * hh;
; #pragma unroll
;                 for (int ci = 0; ci < 8; ++ci) {
;                     s16x4 lo[2][2], hi[2][2];
; #pragma unroll
;                     for (int st = 0; st < 2; ++st)
; #pragma unroll
;                         for (int m2 = 0; m2 < 2; ++m2) { const int off = qb + 32 * m2 * RS + 64 * ci + 32 * st;
;                             lo[st][m2] = *(const LAS s16x4*)(lds + off); hi[st][m2] = *(const LAS s16x4*)(lds + off + 16); }
;                     const bf16x8 bf0 = pack_step<0>(C[ci]), bf1 = pack_step<1>(C[ci]);
;                     __builtin_amdgcn_sched_barrier(0);
; #pragma unroll
;                     for (int m2 = 0; m2 < 2; ++m2) acc2[m2] = MFMA32(join4(lo[0][m2], hi[0][m2]), bf0, acc2[m2]);
; #pragma unroll
;                     for (int m2 = 0; m2 < 2; ++m2) acc2[m2] = MFMA32(join4(lo[1][m2], hi[1][m2]), bf1, acc2[m2]);
;                     __builtin_amdgcn_sched_barrier(0);
;                 }
;             }
.LBB0_393:
	s_nop 4
	v_mov_b32_e32 v128, v192
	v_cvt_pk_bf16_f32 v136, v48, v49
	v_and_b32_e32 v129, 31, v128
	v_lshrrev_b32_e32 v128, 2, v128
	v_mul_u32_u24_e32 v129, 0x210, v129
	v_and_b32_e32 v128, 8, v128
	v_add3_u32 v170, 0, v129, v128
	v_add_u32_e32 v179, 0x4000, v170
	ds_read2_b64 v[128:131], v179 offset0:64 offset1:66
	s_waitcnt lgkmcnt(2)
	ds_read2_b64 v[132:135], v170 offset1:2
	ds_read2_b64 v[164:167], v170 offset0:4 offset1:6
	ds_read2_b64 v[180:183], v179 offset0:68 offset1:70
	v_cvt_pk_bf16_f32 v137, v50, v51
	v_cvt_pk_bf16_f32 v138, v52, v53
	v_cvt_pk_bf16_f32 v139, v54, v55
	v_cvt_pk_bf16_f32 v184, v56, v57
	v_cvt_pk_bf16_f32 v185, v58, v59
	v_cvt_pk_bf16_f32 v186, v60, v61
	v_cvt_pk_bf16_f32 v187, v62, v63
	s_waitcnt lgkmcnt(2)
	v_mfma_f32_32x32x16_bf16 v[144:159], v[132:135], v[136:139], 0
	v_mfma_f32_32x32x16_bf16 v[128:143], v[128:131], v[136:139], 0
	s_waitcnt lgkmcnt(1)
	v_mfma_f32_32x32x16_bf16 v[144:159], v[164:167], v[184:187], v[144:159]
	s_waitcnt lgkmcnt(0)
	v_mfma_f32_32x32x16_bf16 v[128:143], v[180:183], v[184:187], v[128:143]
	ds_read2_b64 v[164:167], v179 offset0:72 offset1:74
	ds_read2_b64 v[180:183], v170 offset0:8 offset1:10
	ds_read2_b64 v[184:187], v170 offset0:12 offset1:14
	ds_read2_b64 v[188:191], v179 offset0:76 offset1:78
	v_cvt_pk_bf16_f32 v194, v32, v33
	v_cvt_pk_bf16_f32 v195, v34, v35
	v_cvt_pk_bf16_f32 v196, v36, v37
	v_cvt_pk_bf16_f32 v197, v38, v39
	v_cvt_pk_bf16_f32 v198, v40, v41
	v_cvt_pk_bf16_f32 v199, v42, v43
	v_cvt_pk_bf16_f32 v200, v44, v45
	v_cvt_pk_bf16_f32 v201, v46, v47
	s_waitcnt lgkmcnt(2)
	v_mfma_f32_32x32x16_bf16 v[144:159], v[180:183], v[194:197], v[144:159]
	v_mfma_f32_32x32x16_bf16 v[128:143], v[164:167], v[194:197], v[128:143]
	s_waitcnt lgkmcnt(1)
	v_mfma_f32_32x32x16_bf16 v[144:159], v[184:187], v[198:201], v[144:159]
	s_waitcnt lgkmcnt(0)
	v_mfma_f32_32x32x16_bf16 v[128:143], v[188:191], v[198:201], v[128:143]
	ds_read2_b64 v[164:167], v179 offset0:80 offset1:82
	ds_read2_b64 v[180:183], v170 offset0:16 offset1:18
	ds_read2_b64 v[184:187], v170 offset0:20 offset1:22
	ds_read2_b64 v[188:191], v179 offset0:84 offset1:86
	v_cvt_pk_bf16_f32 v194, v16, v17
	v_cvt_pk_bf16_f32 v195, v18, v19
	v_cvt_pk_bf16_f32 v196, v20, v21
	v_cvt_pk_bf16_f32 v197, v22, v23
	v_cvt_pk_bf16_f32 v198, v24, v25
	v_cvt_pk_bf16_f32 v199, v26, v27
	v_cvt_pk_bf16_f32 v200, v28, v29
	v_cvt_pk_bf16_f32 v201, v30, v31
	s_waitcnt lgkmcnt(2)
	v_mfma_f32_32x32x16_bf16 v[144:159], v[180:183], v[194:197], v[144:159]
	v_mfma_f32_32x32x16_bf16 v[128:143], v[164:167], v[194:197], v[128:143]
	s_waitcnt lgkmcnt(1)
	v_mfma_f32_32x32x16_bf16 v[144:159], v[184:187], v[198:201], v[144:159]
	s_waitcnt lgkmcnt(0)
	v_mfma_f32_32x32x16_bf16 v[128:143], v[188:191], v[198:201], v[128:143]
	ds_read2_b64 v[164:167], v179 offset0:88 offset1:90
	ds_read2_b64 v[180:183], v170 offset0:24 offset1:26
	ds_read2_b64 v[184:187], v170 offset0:28 offset1:30
	ds_read2_b64 v[188:191], v179 offset0:92 offset1:94
	v_cvt_pk_bf16_f32 v194, v0, v1
	v_cvt_pk_bf16_f32 v195, v2, v3
	v_cvt_pk_bf16_f32 v196, v4, v5
	v_cvt_pk_bf16_f32 v197, v6, v7
	v_cvt_pk_bf16_f32 v198, v8, v9
	v_cvt_pk_bf16_f32 v199, v10, v11
	v_cvt_pk_bf16_f32 v200, v12, v13
	v_cvt_pk_bf16_f32 v201, v14, v15
	s_waitcnt lgkmcnt(2)
	v_mfma_f32_32x32x16_bf16 v[144:159], v[180:183], v[194:197], v[144:159]
	v_mfma_f32_32x32x16_bf16 v[128:143], v[164:167], v[194:197], v[128:143]
	s_waitcnt lgkmcnt(1)
	v_mfma_f32_32x32x16_bf16 v[144:159], v[184:187], v[198:201], v[144:159]
	s_waitcnt lgkmcnt(0)
	v_mfma_f32_32x32x16_bf16 v[128:143], v[188:191], v[198:201], v[128:143]
	ds_read2_b64 v[164:167], v179 offset0:96 offset1:98
	ds_read2_b64 v[180:183], v170 offset0:32 offset1:34
	ds_read2_b64 v[184:187], v170 offset0:36 offset1:38
	ds_read2_b64 v[188:191], v179 offset0:100 offset1:102
	v_cvt_pk_bf16_f32 v194, v64, v65
	v_cvt_pk_bf16_f32 v195, v66, v67
	v_cvt_pk_bf16_f32 v196, v68, v69
	v_cvt_pk_bf16_f32 v197, v70, v71
	v_cvt_pk_bf16_f32 v198, v72, v73
	v_cvt_pk_bf16_f32 v199, v74, v75
	v_cvt_pk_bf16_f32 v200, v76, v77
	v_cvt_pk_bf16_f32 v201, v78, v79
	s_waitcnt lgkmcnt(2)
	v_mfma_f32_32x32x16_bf16 v[144:159], v[180:183], v[194:197], v[144:159]
	v_mfma_f32_32x32x16_bf16 v[128:143], v[164:167], v[194:197], v[128:143]
	s_waitcnt lgkmcnt(1)
	v_mfma_f32_32x32x16_bf16 v[144:159], v[184:187], v[198:201], v[144:159]
	s_waitcnt lgkmcnt(0)
	v_mfma_f32_32x32x16_bf16 v[128:143], v[188:191], v[198:201], v[128:143]
	ds_read2_b64 v[164:167], v179 offset0:104 offset1:106
	ds_read2_b64 v[180:183], v170 offset0:40 offset1:42
	ds_read2_b64 v[184:187], v170 offset0:44 offset1:46
	ds_read2_b64 v[188:191], v179 offset0:108 offset1:110
	v_cvt_pk_bf16_f32 v194, v80, v81
	v_cvt_pk_bf16_f32 v195, v82, v83
	v_cvt_pk_bf16_f32 v196, v84, v85
	v_cvt_pk_bf16_f32 v197, v86, v87
	v_cvt_pk_bf16_f32 v198, v88, v89
	v_cvt_pk_bf16_f32 v199, v90, v91
	v_cvt_pk_bf16_f32 v200, v92, v93
	v_cvt_pk_bf16_f32 v201, v94, v95
	s_waitcnt lgkmcnt(2)
	v_mfma_f32_32x32x16_bf16 v[144:159], v[180:183], v[194:197], v[144:159]
	v_mfma_f32_32x32x16_bf16 v[128:143], v[164:167], v[194:197], v[128:143]
	s_waitcnt lgkmcnt(1)
	v_mfma_f32_32x32x16_bf16 v[144:159], v[184:187], v[198:201], v[144:159]
	s_waitcnt lgkmcnt(0)
	v_mfma_f32_32x32x16_bf16 v[128:143], v[188:191], v[198:201], v[128:143]
	ds_read2_b64 v[164:167], v179 offset0:112 offset1:114
	ds_read2_b64 v[180:183], v170 offset0:48 offset1:50
	ds_read2_b64 v[184:187], v170 offset0:52 offset1:54
	ds_read2_b64 v[188:191], v179 offset0:116 offset1:118
	v_cvt_pk_bf16_f32 v194, v96, v97
	v_cvt_pk_bf16_f32 v195, v98, v99
	v_cvt_pk_bf16_f32 v196, v100, v101
	v_cvt_pk_bf16_f32 v197, v102, v103
	v_cvt_pk_bf16_f32 v198, v104, v105
	v_cvt_pk_bf16_f32 v199, v106, v107
	v_cvt_pk_bf16_f32 v200, v108, v109
	v_cvt_pk_bf16_f32 v201, v110, v111
	s_waitcnt lgkmcnt(2)
	v_mfma_f32_32x32x16_bf16 v[144:159], v[180:183], v[194:197], v[144:159]
	v_mfma_f32_32x32x16_bf16 v[128:143], v[164:167], v[194:197], v[128:143]
	s_waitcnt lgkmcnt(1)
	v_mfma_f32_32x32x16_bf16 v[144:159], v[184:187], v[198:201], v[144:159]
	s_waitcnt lgkmcnt(0)
	v_mfma_f32_32x32x16_bf16 v[128:143], v[188:191], v[198:201], v[128:143]
	ds_read2_b64 v[164:167], v179 offset0:120 offset1:122
	ds_read2_b64 v[180:183], v170 offset0:56 offset1:58
	ds_read2_b64 v[184:187], v170 offset0:60 offset1:62
	ds_read2_b64 v[188:191], v179 offset0:124 offset1:126
	v_cvt_pk_bf16_f32 v194, v112, v113
	v_cvt_pk_bf16_f32 v195, v114, v115
	v_cvt_pk_bf16_f32 v196, v116, v117
	v_cvt_pk_bf16_f32 v197, v118, v119
	v_cvt_pk_bf16_f32 v198, v120, v121
	v_cvt_pk_bf16_f32 v199, v122, v123
	v_cvt_pk_bf16_f32 v200, v124, v125
	v_cvt_pk_bf16_f32 v201, v126, v127
	s_waitcnt lgkmcnt(2)
	v_mfma_f32_32x32x16_bf16 v[144:159], v[180:183], v[194:197], v[144:159]
	v_mfma_f32_32x32x16_bf16 v[128:143], v[164:167], v[194:197], v[128:143]
	s_waitcnt lgkmcnt(1)
	v_mfma_f32_32x32x16_bf16 v[144:159], v[184:187], v[198:201], v[144:159]
	s_waitcnt lgkmcnt(0)
	v_mfma_f32_32x32x16_bf16 v[128:143], v[188:191], v[198:201], v[128:143]
	v_mov_b32_e32 v179, v192
	s_barrier
; #define LAS __attribute__((address_space(3)))
; DI unsigned pk2(float a, float b) { f32x2 v = {a, b}; bf2_t r = __builtin_convertvector(v, bf2_t); return __builtin_bit_cast(unsigned, r); }
; DI int opq(int x) { asm volatile("" : "+v"(x)); return x; }
; DI bf16x8 join4(const s16x4& lo, const s16x4& hi) { return __builtin_shufflevector(lo, hi, 0, 1, 2, 3, 4, 5, 6, 7); }
; DI void phase_mlstm(const Params& p, unsigned char* shm, const int vb) {
;     ...
;             {
;                 const int lane = opq(threadIdx.x) & 63, l32 = lane & 31, hh = lane >> 5, q4 = (lane & 15) >> 2, p4 = lane & 3, blk = (lane >> 4) & 1;
; #pragma unroll
;                 for (int m = 0; m < 2; ++m)
; #pragma unroll
;                     for (int g = 0; g < 4; ++g) { const f32x4 d4 = *(const LAS f32x4*)(dec + 32 * m + 8 * g + 4 * hh);
; #pragma unroll
;                         for (int e = 0; e < 4; ++e) acc2[m][4 * g + e] *= d4[e]; }
;                 const int vb = VI + (8 * hh + q4) * RS + (32 * w + 16 * blk) * 2 + 8 * p4, sb = SMI + l32 * SMS + 16 * hh;
; #pragma unroll
;                 for (int kk = 0; kk < 4; ++kk) {
;                     const s16x4 lo = TRRD(lds + vb + 16 * kk * RS), hi = TRRD(lds + vb + 16 * kk * RS + 4 * RS);
;                     const bf16x8 bf = join4(lo, hi);
; #pragma unroll
;                     for (int m = 0; m < 2; ++m) { const bf16x8 af = *(const LAS bf16x8*)(lds + sb + 32 * m * SMS + 32 * kk); acc2[m] = MFMA32(af, bf, acc2[m]); }
;                 }
;                 const int hb = QI + 4 * hh * RS + (32 * w + l32) * 2;
; #pragma unroll
;                 for (int m = 0; m < 2; ++m)
; #pragma unroll
;                     for (int g = 0; g < 4; ++g) {
;                         const int rb = 32 * m + 8 * g;
;                         const f32x4 d4 = *(const LAS f32x4*)(dec + rb + 4 * hh), n4 = *(const LAS f32x4*)(qn + rb + 4 * hh), s4 = *(const LAS f32x4*)(rsum + rb + 4 * hh), f4 = *(const LAS f32x4*)(flr + rb + 4 * hh);
; #pragma unroll
;                         for (int e = 0; e < 4; ++e) {
;                             const float den = d4[e] * n4[e] + s4[e];
;                             const float val = acc2[m][4 * g + e] * __builtin_amdgcn_rcpf(fmaxf(fabsf(den), f4[e]));
;                             *(LAS bf16_t*)(lds + hb + (rb + e) * RS) = (bf16_t)(pk2(val, 0.f) & 0xffffu);
;                         }
;                     }
	s_mov_b32 s2, 0x12900
	v_bfe_u32 v193, v179, 5, 1
	v_lshl_add_u32 v199, v193, 4, 0
	v_add_u32_e32 v170, 0x1dd00, v199
	ds_read_b128 v[164:167], v170
	ds_read_b128 v[180:183], v170 offset:32
	ds_read_b128 v[184:187], v170 offset:64
	ds_read_b128 v[188:191], v170 offset:96
	v_bfe_u32 v198, v179, 2, 2
	s_waitcnt lgkmcnt(3)
	v_pk_mul_f32 v[146:147], v[146:147], v[166:167]
	s_waitcnt lgkmcnt(2)
	v_pk_mul_f32 v[148:149], v[148:149], v[180:181]
	s_waitcnt lgkmcnt(1)
	v_pk_mul_f32 v[152:153], v[152:153], v[184:185]
	s_waitcnt lgkmcnt(0)
	v_pk_mul_f32 v[156:157], v[156:157], v[188:189]
	v_pk_mul_f32 v[158:159], v[158:159], v[190:191]
	v_pk_mul_f32 v[154:155], v[154:155], v[186:187]
	v_pk_mul_f32 v[150:151], v[150:151], v[182:183]
	ds_read_b128 v[180:183], v170 offset:128
	ds_read_b128 v[184:187], v170 offset:160
	ds_read_b128 v[188:191], v170 offset:192
	ds_read_b128 v[194:197], v170 offset:224
	v_pk_mul_f32 v[144:145], v[144:145], v[164:165]
	s_waitcnt lgkmcnt(3)
	v_pk_mul_f32 v[128:129], v[128:129], v[180:181]
	v_lshl_or_b32 v180, v193, 3, v198
	v_and_or_b32 v181, v179, 16, s23
	s_waitcnt lgkmcnt(0)
	v_pk_mul_f32 v[140:141], v[140:141], v[194:195]
	v_and_b32_e32 v194, 31, v179
	v_mul_u32_u24_e32 v180, 0x210, v180
	v_lshlrev_b32_e32 v181, 1, v181
	v_lshlrev_b32_e32 v179, 3, v179
	v_and_b32_e32 v179, 24, v179
	v_add3_u32 v180, 0, v180, v181
	v_pk_mul_f32 v[130:131], v[130:131], v[182:183]
	v_mul_u32_u24_e32 v182, 0x90, v194
	v_add3_u32 v179, v180, v179, s2
	s_mov_b32 s2, 0x1ad00
	v_pk_mul_f32 v[136:137], v[136:137], v[188:189]
	v_pk_mul_f32 v[132:133], v[132:133], v[184:185]
	v_pk_mul_f32 v[138:139], v[138:139], v[190:191]
	v_pk_mul_f32 v[134:135], v[134:135], v[186:187]
	v_add3_u32 v195, v199, v182, s2
	ds_read_b64_tr_b16 v[180:181], v179
	ds_read_b64_tr_b16 v[182:183], v179 offset:2112
	ds_read_b128 v[184:187], v195
	ds_read_b128 v[188:191], v195 offset:32
	s_waitcnt lgkmcnt(1)
	v_mfma_f32_32x32x16_bf16 v[144:159], v[184:187], v[180:183], v[144:159]
	ds_read_b128 v[184:187], v195 offset:4608
	v_mul_f32_e64 v142, v142, v196
	v_mul_f32_e64 v143, v143, v197
	s_waitcnt lgkmcnt(0)
	s_nop 0
	v_mfma_f32_32x32x16_bf16 v[128:143], v[184:187], v[180:183], v[128:143]
	ds_read_b64_tr_b16 v[180:181], v179 offset:8448
	ds_read_b64_tr_b16 v[182:183], v179 offset:10560
	ds_read_b128 v[184:187], v195 offset:4640
	s_waitcnt lgkmcnt(1)
	v_mfma_f32_32x32x16_bf16 v[144:159], v[188:191], v[180:183], v[144:159]
	s_waitcnt lgkmcnt(0)
	v_mfma_f32_32x32x16_bf16 v[128:143], v[184:187], v[180:183], v[128:143]
	ds_read_b64_tr_b16 v[180:181], v179 offset:16896
	ds_read_b64_tr_b16 v[182:183], v179 offset:19008
	ds_read_b128 v[184:187], v195 offset:64
	s_waitcnt lgkmcnt(0)
	v_mfma_f32_32x32x16_bf16 v[144:159], v[184:187], v[180:183], v[144:159]
	ds_read_b128 v[184:187], v195 offset:4672
	s_waitcnt lgkmcnt(0)
	v_mfma_f32_32x32x16_bf16 v[128:143], v[184:187], v[180:183], v[128:143]
	ds_read_b64_tr_b16 v[180:181], v179 offset:25344
	ds_read_b64_tr_b16 v[182:183], v179 offset:27456
	ds_read_b128 v[184:187], v195 offset:96
	v_mul_u32_u24_e32 v179, 0x840, v193
	s_waitcnt lgkmcnt(0)
	v_mfma_f32_32x32x16_bf16 v[144:159], v[184:187], v[180:183], v[144:159]
	ds_read_b128 v[184:187], v195 offset:4704
	s_waitcnt lgkmcnt(0)
	v_mfma_f32_32x32x16_bf16 v[128:143], v[184:187], v[180:183], v[128:143]
	v_or_b32_e32 v180, s23, v194
	v_lshlrev_b32_e32 v183, 1, v180
	v_add_u32_e32 v180, 0x1d900, v199
	v_add_u32_e32 v181, 0x1da00, v199
	v_add_u32_e32 v182, 0x1de00, v199
	ds_read_b128 v[184:187], v180
	ds_read_b128 v[188:191], v181
	ds_read_b128 v[194:197], v182
	v_add3_u32 v179, 0, v179, v183
	s_waitcnt lgkmcnt(1)
	v_fma_f32 v164, v164, v184, v188
	s_waitcnt lgkmcnt(0)
	v_max_f32_e32 v183, v194, v194
	v_max_f32_e64 v164, |v164|, v183
	v_rcp_f32_e32 v164, v164
	v_fmac_f32_e32 v191, v167, v187
	v_mul_f32_e32 v144, v144, v164
	v_cvt_pk_bf16_f32 v144, v144, s0
	ds_write_b16 v179, v144
	v_fma_f32 v144, v165, v185, v189
	v_max_f32_e32 v164, v195, v195
	v_max_f32_e64 v144, |v144|, v164
	v_rcp_f32_e32 v144, v144
	s_nop 0
	v_mul_f32_e32 v144, v145, v144
	v_cvt_pk_bf16_f32 v144, v144, s0
	ds_write_b16 v179, v144 offset:528
	v_fma_f32 v144, v166, v186, v190
	v_max_f32_e32 v145, v196, v196
	v_max_f32_e64 v144, |v144|, v145
	v_rcp_f32_e32 v144, v144
	s_nop 0
	v_mul_f32_e32 v144, v146, v144
	v_cvt_pk_bf16_f32 v144, v144, s0
	ds_write_b16 v179, v144 offset:1056
	v_max_f32_e32 v144, v197, v197
	v_max_f32_e64 v144, |v191|, v144
	v_rcp_f32_e32 v144, v144
	s_nop 0
	v_mul_f32_e32 v144, v147, v144
	v_cvt_pk_bf16_f32 v144, v144, s0
	ds_write_b16 v179, v144 offset:1584
	ds_read_b128 v[144:147], v170 offset:32
	ds_read_b128 v[164:167], v180 offset:32
	ds_read_b128 v[184:187], v181 offset:32
	ds_read_b128 v[188:191], v182 offset:32
	s_waitcnt lgkmcnt(1)
	v_fma_f32 v144, v144, v164, v184
	s_waitcnt lgkmcnt(0)
	v_max_f32_e32 v164, v188, v188
	v_max_f32_e64 v144, |v144|, v164
	v_rcp_f32_e32 v144, v144
	v_fmac_f32_e32 v187, v147, v167
	v_mul_f32_e32 v144, v148, v144
	v_cvt_pk_bf16_f32 v144, v144, s0
	ds_write_b16 v179, v144 offset:4224
	v_fma_f32 v144, v145, v165, v185
	v_max_f32_e32 v145, v189, v189
	v_max_f32_e64 v144, |v144|, v145
	v_rcp_f32_e32 v144, v144
	v_max_f32_e32 v145, v190, v190
	v_mul_f32_e32 v144, v149, v144
	v_cvt_pk_bf16_f32 v144, v144, s0
	ds_write_b16 v179, v144 offset:4752
	v_fma_f32 v144, v146, v166, v186
	v_max_f32_e64 v144, |v144|, v145
	v_rcp_f32_e32 v144, v144
	s_nop 0
	v_mul_f32_e32 v144, v150, v144
	v_cvt_pk_bf16_f32 v144, v144, s0
	ds_write_b16 v179, v144 offset:5280
	v_max_f32_e32 v144, v191, v191
	v_max_f32_e64 v144, |v187|, v144
	v_rcp_f32_e32 v144, v144
	s_nop 0
	v_mul_f32_e32 v144, v151, v144
	v_cvt_pk_bf16_f32 v144, v144, s0
	ds_write_b16 v179, v144 offset:5808
	ds_read_b128 v[144:147], v170 offset:64
	ds_read_b128 v[148:151], v180 offset:64
	ds_read_b128 v[164:167], v181 offset:64
	ds_read_b128 v[184:187], v182 offset:64
	s_waitcnt lgkmcnt(1)
; #define LAS __attribute__((address_space(3)))
; DI unsigned pk2(float a, float b) { f32x2 v = {a, b}; bf2_t r = __builtin_convertvector(v, bf2_t); return __builtin_bit_cast(unsigned, r); }
; DI void phase_mlstm(const Params& p, unsigned char* shm, const int vb) {
;     ...
;                 const int hb = QI + 4 * hh * RS + (32 * w + l32) * 2;
; #pragma unroll
;                 for (int m = 0; m < 2; ++m)
; #pragma unroll
;                     for (int g = 0; g < 4; ++g) {
;                         const int rb = 32 * m + 8 * g;
;                         const f32x4 d4 = *(const LAS f32x4*)(dec + rb + 4 * hh), n4 = *(const LAS f32x4*)(qn + rb + 4 * hh), s4 = *(const LAS f32x4*)(rsum + rb + 4 * hh), f4 = *(const LAS f32x4*)(flr + rb + 4 * hh);
; #pragma unroll
;                         for (int e = 0; e < 4; ++e) {
;                             const float den = d4[e] * n4[e] + s4[e];
;                             const float val = acc2[m][4 * g + e] * __builtin_amdgcn_rcpf(fmaxf(fabsf(den), f4[e]));
;                             *(LAS bf16_t*)(lds + hb + (rb + e) * RS) = (bf16_t)(pk2(val, 0.f) & 0xffffu);
;                         }
;                     }
	v_fma_f32 v144, v144, v148, v164
	s_waitcnt lgkmcnt(0)
	v_max_f32_e32 v148, v184, v184
	v_max_f32_e64 v144, |v144|, v148
	v_rcp_f32_e32 v144, v144
	v_fmac_f32_e32 v167, v147, v151
	v_mul_f32_e32 v144, v152, v144
	v_cvt_pk_bf16_f32 v144, v144, s0
	ds_write_b16 v179, v144 offset:8448
	v_fma_f32 v144, v145, v149, v165
	v_max_f32_e32 v145, v185, v185
	v_max_f32_e64 v144, |v144|, v145
	v_rcp_f32_e32 v144, v144
	v_max_f32_e32 v145, v186, v186
	v_mul_f32_e32 v144, v153, v144
	v_cvt_pk_bf16_f32 v144, v144, s0
	ds_write_b16 v179, v144 offset:8976
	v_fma_f32 v144, v146, v150, v166
	v_max_f32_e64 v144, |v144|, v145
	v_rcp_f32_e32 v144, v144
	s_nop 0
	v_mul_f32_e32 v144, v154, v144
	v_cvt_pk_bf16_f32 v144, v144, s0
	ds_write_b16 v179, v144 offset:9504
	v_max_f32_e32 v144, v187, v187
	v_max_f32_e64 v144, |v167|, v144
	v_rcp_f32_e32 v144, v144
	s_nop 0
	v_mul_f32_e32 v144, v155, v144
	v_cvt_pk_bf16_f32 v144, v144, s0
	ds_write_b16 v179, v144 offset:10032
	ds_read_b128 v[144:147], v170 offset:96
	ds_read_b128 v[148:151], v180 offset:96
	ds_read_b128 v[152:155], v181 offset:96
	ds_read_b128 v[164:167], v182 offset:96
	s_waitcnt lgkmcnt(1)
	v_fma_f32 v144, v144, v148, v152
	s_waitcnt lgkmcnt(0)
	v_max_f32_e32 v148, v164, v164
	v_max_f32_e64 v144, |v144|, v148
	v_rcp_f32_e32 v144, v144
	v_fmac_f32_e32 v155, v147, v151
	v_mul_f32_e32 v144, v156, v144
	v_cvt_pk_bf16_f32 v144, v144, s0
	ds_write_b16 v179, v144 offset:12672
	v_fma_f32 v144, v145, v149, v153
	v_max_f32_e32 v145, v165, v165
	v_max_f32_e64 v144, |v144|, v145
	v_rcp_f32_e32 v144, v144
	v_max_f32_e32 v145, v166, v166
	v_mul_f32_e32 v144, v157, v144
	v_cvt_pk_bf16_f32 v144, v144, s0
	ds_write_b16 v179, v144 offset:13200
	v_fma_f32 v144, v146, v150, v154
	v_max_f32_e64 v144, |v144|, v145
	v_rcp_f32_e32 v144, v144
	s_nop 0
	v_mul_f32_e32 v144, v158, v144
	v_cvt_pk_bf16_f32 v144, v144, s0
	ds_write_b16 v179, v144 offset:13728
	v_max_f32_e32 v144, v167, v167
	v_max_f32_e64 v144, |v155|, v144
	v_rcp_f32_e32 v144, v144
	s_nop 0
	v_mul_f32_e32 v144, v159, v144
	v_cvt_pk_bf16_f32 v144, v144, s0
	ds_write_b16 v179, v144 offset:14256
	ds_read_b128 v[144:147], v170 offset:128
	ds_read_b128 v[148:151], v180 offset:128
	ds_read_b128 v[152:155], v181 offset:128
	ds_read_b128 v[156:159], v182 offset:128
	s_waitcnt lgkmcnt(1)
	v_fma_f32 v144, v144, v148, v152
	s_waitcnt lgkmcnt(0)
	v_max_f32_e32 v148, v156, v156
	v_max_f32_e64 v144, |v144|, v148
	v_rcp_f32_e32 v144, v144
	v_fmac_f32_e32 v155, v147, v151
	v_mul_f32_e32 v128, v128, v144
	v_cvt_pk_bf16_f32 v128, v128, s0
	ds_write_b16 v179, v128 offset:16896
	v_fma_f32 v128, v145, v149, v153
	v_max_f32_e32 v144, v157, v157
	v_max_f32_e64 v128, |v128|, v144
	v_rcp_f32_e32 v128, v128
	s_nop 0
	v_mul_f32_e32 v128, v129, v128
	v_cvt_pk_bf16_f32 v128, v128, s0
	ds_write_b16 v179, v128 offset:17424
	v_fma_f32 v128, v146, v150, v154
	v_max_f32_e32 v129, v158, v158
	v_max_f32_e64 v128, |v128|, v129
	v_rcp_f32_e32 v128, v128
	s_nop 0
	v_mul_f32_e32 v128, v130, v128
	v_cvt_pk_bf16_f32 v128, v128, s0
	ds_write_b16 v179, v128 offset:17952
	v_max_f32_e32 v128, v159, v159
	v_max_f32_e64 v128, |v155|, v128
	v_rcp_f32_e32 v128, v128
	s_nop 0
	v_mul_f32_e32 v128, v131, v128
	v_cvt_pk_bf16_f32 v128, v128, s0
	ds_write_b16 v179, v128 offset:18480
	ds_read_b128 v[128:131], v170 offset:160
	ds_read_b128 v[144:147], v180 offset:160
	ds_read_b128 v[148:151], v181 offset:160
	ds_read_b128 v[152:155], v182 offset:160
	s_waitcnt lgkmcnt(1)
	v_fma_f32 v128, v128, v144, v148
	s_waitcnt lgkmcnt(0)
	v_max_f32_e32 v144, v152, v152
	v_max_f32_e64 v128, |v128|, v144
	v_rcp_f32_e32 v128, v128
	v_fmac_f32_e32 v151, v131, v147
	v_mul_f32_e32 v128, v132, v128
	v_cvt_pk_bf16_f32 v128, v128, s0
	ds_write_b16 v179, v128 offset:21120
	v_fma_f32 v128, v129, v145, v149
	v_max_f32_e32 v129, v153, v153
	v_max_f32_e64 v128, |v128|, v129
	v_rcp_f32_e32 v128, v128
	v_max_f32_e32 v129, v154, v154
	v_mul_f32_e32 v128, v133, v128
	v_cvt_pk_bf16_f32 v128, v128, s0
	ds_write_b16 v179, v128 offset:21648
	v_fma_f32 v128, v130, v146, v150
	v_max_f32_e64 v128, |v128|, v129
	v_rcp_f32_e32 v128, v128
	s_nop 0
	v_mul_f32_e32 v128, v134, v128
	v_cvt_pk_bf16_f32 v128, v128, s0
	ds_write_b16 v179, v128 offset:22176
	v_max_f32_e32 v128, v155, v155
	v_max_f32_e64 v128, |v151|, v128
	v_rcp_f32_e32 v128, v128
	s_nop 0
	v_mul_f32_e32 v128, v135, v128
	v_cvt_pk_bf16_f32 v128, v128, s0
	ds_write_b16 v179, v128 offset:22704
	ds_read_b128 v[128:131], v170 offset:192
	ds_read_b128 v[132:135], v180 offset:192
	ds_read_b128 v[144:147], v181 offset:192
	ds_read_b128 v[148:151], v182 offset:192
	s_waitcnt lgkmcnt(1)
	v_fma_f32 v128, v128, v132, v144
	s_waitcnt lgkmcnt(0)
	v_max_f32_e32 v132, v148, v148
	v_max_f32_e64 v128, |v128|, v132
	v_rcp_f32_e32 v128, v128
	v_fmac_f32_e32 v147, v131, v135
	v_mul_f32_e32 v128, v136, v128
	v_cvt_pk_bf16_f32 v128, v128, s0
	ds_write_b16 v179, v128 offset:25344
	v_fma_f32 v128, v129, v133, v145
	v_max_f32_e32 v129, v149, v149
	v_max_f32_e64 v128, |v128|, v129
	v_rcp_f32_e32 v128, v128
	v_max_f32_e32 v129, v150, v150
	v_mul_f32_e32 v128, v137, v128
	v_cvt_pk_bf16_f32 v128, v128, s0
	ds_write_b16 v179, v128 offset:25872
	v_fma_f32 v128, v130, v134, v146
	v_max_f32_e64 v128, |v128|, v129
	v_rcp_f32_e32 v128, v128
	s_nop 0
	v_mul_f32_e32 v128, v138, v128
	v_cvt_pk_bf16_f32 v128, v128, s0
	ds_write_b16 v179, v128 offset:26400
	v_max_f32_e32 v128, v151, v151
	v_max_f32_e64 v128, |v147|, v128
	v_rcp_f32_e32 v128, v128
	s_nop 0
	v_mul_f32_e32 v128, v139, v128
	v_cvt_pk_bf16_f32 v128, v128, s0
	ds_write_b16 v179, v128 offset:26928
	ds_read_b128 v[128:131], v170 offset:224
	ds_read_b128 v[132:135], v180 offset:224
	ds_read_b128 v[136:139], v181 offset:224
	ds_read_b128 v[144:147], v182 offset:224
	s_waitcnt lgkmcnt(1)
; #define LAS __attribute__((address_space(3)))
; DI unsigned pk2(float a, float b) { f32x2 v = {a, b}; bf2_t r = __builtin_convertvector(v, bf2_t); return __builtin_bit_cast(unsigned, r); }
; DI int opq(int x) { asm volatile("" : "+v"(x)); return x; }
; DI u32x4 pack8f(const float (&f)[8]) { u32x4 r; r[0] = pk2(f[0], f[1]); r[1] = pk2(f[2], f[3]); r[2] = pk2(f[4], f[5]); r[3] = pk2(f[6], f[7]); return r; }
; DI bf16x8 join4(const s16x4& lo, const s16x4& hi) { return __builtin_shufflevector(lo, hi, 0, 1, 2, 3, 4, 5, 6, 7); }
; #define TRRD(ptr) __builtin_amdgcn_ds_read_tr16_b64_v4i16((LAS s16x4*)(ptr))
; DI void phase_mlstm(const Params& p, unsigned char* shm, const int vb) {
;     ...
;                     for (int g = 0; g < 4; ++g) {
;                         const int rb = 32 * m + 8 * g;
;                         const f32x4 d4 = *(const LAS f32x4*)(dec + rb + 4 * hh), n4 = *(const LAS f32x4*)(qn + rb + 4 * hh), s4 = *(const LAS f32x4*)(rsum + rb + 4 * hh), f4 = *(const LAS f32x4*)(flr + rb + 4 * hh);
; #pragma unroll
;                         for (int e = 0; e < 4; ++e) {
;                             const float den = d4[e] * n4[e] + s4[e];
;                             const float val = acc2[m][4 * g + e] * __builtin_amdgcn_rcpf(fmaxf(fabsf(den), f4[e]));
;                             *(LAS bf16_t*)(lds + hb + (rb + e) * RS) = (bf16_t)(pk2(val, 0.f) & 0xffffu);
;                         }
;                     }
;     ...
;             {
;                 const int lane = opq(threadIdx.x) & 63, hh = lane >> 5, q4 = (lane & 15) >> 2, p4 = lane & 3, blk = (lane >> 4) & 1;
;                 const int tb = (8 * hh + q4) * RS + 32 * blk + 8 * p4;
;                 bf16x8 bw[4];
; #pragma unroll
;                 for (int kk = 0; kk < 4; ++kk) { const int voff = VI + tb + 64 * w + 16 * kk * RS;
;                     const bf16x8 raw = join4(TRRD(lds + voff), TRRD(lds + voff + 4 * RS));
;                     const f32x4 w0 = *(const LAS f32x4*)(wls + 16 * kk + 8 * hh), w1 = *(const LAS f32x4*)(wls + 16 * kk + 8 * hh + 4);
;                     float f[8]; unpack8(__builtin_bit_cast(u32x4, raw), f);
; #pragma unroll
;                     for (int e = 0; e < 4; ++e) { f[e] *= w0[e]; f[4 + e] *= w1[e]; }
;                     bw[kk] = __builtin_bit_cast(bf16x8, pack8f(f)); }
	v_fma_f32 v128, v128, v132, v136
	s_waitcnt lgkmcnt(0)
	v_max_f32_e32 v132, v144, v144
	v_max_f32_e64 v128, |v128|, v132
	v_rcp_f32_e32 v128, v128
	v_fmac_f32_e32 v139, v131, v135
	v_mul_f32_e32 v128, v140, v128
	v_cvt_pk_bf16_f32 v128, v128, s0
	ds_write_b16 v179, v128 offset:29568
	v_fma_f32 v128, v129, v133, v137
	v_max_f32_e32 v129, v145, v145
	v_max_f32_e64 v128, |v128|, v129
	v_rcp_f32_e32 v128, v128
	v_max_f32_e32 v129, v146, v146
	v_mul_f32_e32 v128, v141, v128
	v_cvt_pk_bf16_f32 v128, v128, s0
	ds_write_b16 v179, v128 offset:30096
	v_fma_f32 v128, v130, v134, v138
	v_max_f32_e64 v128, |v128|, v129
	v_rcp_f32_e32 v128, v128
	s_nop 0
	v_mul_f32_e32 v128, v142, v128
	v_cvt_pk_bf16_f32 v128, v128, s0
	ds_write_b16 v179, v128 offset:30624
	v_max_f32_e32 v128, v147, v147
	v_max_f32_e64 v128, |v139|, v128
	v_rcp_f32_e32 v128, v128
	s_nop 0
	v_mul_f32_e32 v128, v143, v128
	v_cvt_pk_bf16_f32 v128, v128, s0
	ds_write_b16 v179, v128 offset:31152
	v_mov_b32_e32 v128, v192
	v_pk_mul_f32 v[62:63], v[62:63], v[168:169] op_sel_hi:[1,0]
	v_lshrrev_b32_e32 v129, 2, v128
	v_lshlrev_b32_e32 v131, 3, v128
	v_and_b32_e32 v129, 11, v129
	v_lshlrev_b32_e32 v130, 1, v128
	v_and_b32_e32 v131, 24, v131
	v_mul_u32_u24_e32 v129, 0x210, v129
	v_and_b32_e32 v130, 32, v130
	v_add_u32_e32 v131, 0, v131
	v_add3_u32 v144, v131, v130, v129
	v_add_u32_e32 v129, s33, v144
	v_and_b32_e32 v128, 32, v128
	v_add_u32_e32 v145, 0x12900, v129
	v_add_u32_e32 v128, 0, v128
	v_add_u32_e32 v156, 0x1df00, v128
	ds_read_b64_tr_b16 v[136:137], v145
	ds_read_b128 v[128:131], v156
	ds_read_b128 v[132:135], v156 offset:16
	ds_read_b64_tr_b16 v[138:139], v145 offset:2112
	ds_read_b64_tr_b16 v[140:141], v145 offset:8448
	ds_read_b64_tr_b16 v[142:143], v145 offset:10560
	s_waitcnt lgkmcnt(5)
	v_lshlrev_b32_e32 v146, 16, v136
	v_and_b32_e32 v147, 0xffff0000, v136
	s_waitcnt lgkmcnt(4)
	v_pk_mul_f32 v[128:129], v[128:129], v[146:147]
	s_waitcnt lgkmcnt(2)
	v_lshlrev_b32_e32 v146, 16, v138
	v_and_b32_e32 v147, 0xffff0000, v138
	v_lshlrev_b32_e32 v136, 16, v137
	v_and_b32_e32 v137, 0xffff0000, v137
	v_pk_mul_f32 v[132:133], v[132:133], v[146:147]
	v_pk_mul_f32 v[130:131], v[130:131], v[136:137]
	v_lshlrev_b32_e32 v136, 16, v139
	v_and_b32_e32 v137, 0xffff0000, v139
	v_pk_mul_f32 v[136:137], v[134:135], v[136:137]
	v_cvt_pk_bf16_f32 v128, v128, v129
	v_cvt_pk_bf16_f32 v129, v130, v131
	v_cvt_pk_bf16_f32 v130, v132, v133
	ds_read_b128 v[132:135], v156 offset:64
	v_cvt_pk_bf16_f32 v131, v136, v137
	ds_read_b128 v[136:139], v156 offset:80
	s_waitcnt lgkmcnt(3)
	v_lshlrev_b32_e32 v146, 16, v140
	v_and_b32_e32 v147, 0xffff0000, v140
	v_lshlrev_b32_e32 v140, 16, v141
	v_and_b32_e32 v141, 0xffff0000, v141
	s_waitcnt lgkmcnt(1)
	v_pk_mul_f32 v[132:133], v[132:133], v[146:147]
	v_lshlrev_b32_e32 v146, 16, v142
	v_and_b32_e32 v147, 0xffff0000, v142
	v_pk_mul_f32 v[134:135], v[134:135], v[140:141]
	v_lshlrev_b32_e32 v140, 16, v143
	v_and_b32_e32 v141, 0xffff0000, v143
	s_waitcnt lgkmcnt(0)
	v_pk_mul_f32 v[136:137], v[136:137], v[146:147]
	v_pk_mul_f32 v[138:139], v[138:139], v[140:141]
	v_cvt_pk_bf16_f32 v132, v132, v133
	v_cvt_pk_bf16_f32 v133, v134, v135
	v_cvt_pk_bf16_f32 v134, v136, v137
	v_cvt_pk_bf16_f32 v135, v138, v139
	ds_read_b64_tr_b16 v[146:147], v145 offset:16896
	ds_read_b128 v[136:139], v156 offset:128
	ds_read_b128 v[140:143], v156 offset:144
	ds_read_b64_tr_b16 v[148:149], v145 offset:19008
	ds_read_b64_tr_b16 v[150:151], v145 offset:25344
	ds_read_b64_tr_b16 v[152:153], v145 offset:27456
	s_waitcnt lgkmcnt(5)
	v_lshlrev_b32_e32 v154, 16, v146
	v_and_b32_e32 v155, 0xffff0000, v146
	s_waitcnt lgkmcnt(4)
	v_pk_mul_f32 v[136:137], v[136:137], v[154:155]
	s_waitcnt lgkmcnt(2)
	v_lshlrev_b32_e32 v154, 16, v148
	v_and_b32_e32 v155, 0xffff0000, v148
	v_lshlrev_b32_e32 v146, 16, v147
	v_and_b32_e32 v147, 0xffff0000, v147
	v_pk_mul_f32 v[140:141], v[140:141], v[154:155]
	v_pk_mul_f32 v[138:139], v[138:139], v[146:147]
	v_lshlrev_b32_e32 v146, 16, v149
	v_and_b32_e32 v147, 0xffff0000, v149
	v_pk_mul_f32 v[146:147], v[142:143], v[146:147]
	v_cvt_pk_bf16_f32 v136, v136, v137
	v_cvt_pk_bf16_f32 v137, v138, v139
	v_cvt_pk_bf16_f32 v138, v140, v141
	ds_read_b128 v[140:143], v156 offset:192
	v_cvt_pk_bf16_f32 v139, v146, v147
	ds_read_b128 v[146:149], v156 offset:208
	s_waitcnt lgkmcnt(3)
	v_lshlrev_b32_e32 v154, 16, v150
	v_and_b32_e32 v155, 0xffff0000, v150
	v_lshlrev_b32_e32 v150, 16, v151
	v_and_b32_e32 v151, 0xffff0000, v151
	s_waitcnt lgkmcnt(1)
	v_pk_mul_f32 v[140:141], v[140:141], v[154:155]
	v_lshlrev_b32_e32 v154, 16, v152
	v_and_b32_e32 v155, 0xffff0000, v152
	v_pk_mul_f32 v[142:143], v[142:143], v[150:151]
	v_lshlrev_b32_e32 v150, 16, v153
	v_and_b32_e32 v151, 0xffff0000, v153
	s_waitcnt lgkmcnt(0)
	v_pk_mul_f32 v[146:147], v[146:147], v[154:155]
	v_pk_mul_f32 v[148:149], v[148:149], v[150:151]
	v_cvt_pk_bf16_f32 v140, v140, v141
	v_cvt_pk_bf16_f32 v141, v142, v143
	v_cvt_pk_bf16_f32 v142, v146, v147
	v_cvt_pk_bf16_f32 v143, v148, v149
	ds_read_b64_tr_b16 v[146:147], v144 offset:33792
	ds_read_b64_tr_b16 v[148:149], v144 offset:35904
	ds_read_b64_tr_b16 v[150:151], v144 offset:42240
	ds_read_b64_tr_b16 v[152:153], v144 offset:44352
	ds_read_b64_tr_b16 v[154:155], v144 offset:50688
	ds_read_b64_tr_b16 v[156:157], v144 offset:52800
	ds_read_b64_tr_b16 v[164:165], v144 offset:59136
	ds_read_b64_tr_b16 v[166:167], v144 offset:61248
	v_pk_mul_f32 v[60:61], v[60:61], v[168:169] op_sel_hi:[1,0]
	v_pk_mul_f32 v[58:59], v[58:59], v[168:169] op_sel_hi:[1,0]
	v_pk_mul_f32 v[56:57], v[56:57], v[168:169] op_sel_hi:[1,0]
	v_pk_mul_f32 v[54:55], v[54:55], v[168:169] op_sel_hi:[1,0]
	v_pk_mul_f32 v[52:53], v[52:53], v[168:169] op_sel_hi:[1,0]
	v_pk_mul_f32 v[50:51], v[50:51], v[168:169] op_sel_hi:[1,0]
	v_pk_mul_f32 v[48:49], v[48:49], v[168:169] op_sel_hi:[1,0]
	s_waitcnt lgkmcnt(6)
; DI bf16x8 join4(const s16x4& lo, const s16x4& hi) { return __builtin_shufflevector(lo, hi, 0, 1, 2, 3, 4, 5, 6, 7); }
; #define MFMA32(a, b, c) __builtin_amdgcn_mfma_f32_32x32x16_bf16((a), (b), (c), 0, 0, 0)
; #define TRRD(ptr) __builtin_amdgcn_ds_read_tr16_b64_v4i16((LAS s16x4*)(ptr))
; DI void phase_mlstm(const Params& p, unsigned char* shm, const int vb) {
;     ...
; #pragma unroll
;                 for (int ci = 0; ci < 8; ++ci) {
;                     bf16x8 ka[4];
; #pragma unroll
;                     for (int kk = 0; kk < 4; ++kk) { const int koff = KI + tb + 64 * ci + 16 * kk * RS; ka[kk] = join4(TRRD(lds + koff), TRRD(lds + koff + 4 * RS)); }
; #pragma unroll
;                     for (int e = 0; e < 16; ++e) C[ci][e] *= d_last;
;                     __builtin_amdgcn_sched_barrier(0);
; #pragma unroll
;                     for (int kk = 0; kk < 4; ++kk) C[ci] = MFMA32(ka[kk], bw[kk], C[ci]);
;                     __builtin_amdgcn_sched_barrier(0);
;                 }
	s_nop 0
	v_mfma_f32_32x32x16_bf16 v[48:63], v[146:149], v[128:131], v[48:63]
	s_waitcnt lgkmcnt(4)
	v_mfma_f32_32x32x16_bf16 v[48:63], v[150:153], v[132:135], v[48:63]
	s_waitcnt lgkmcnt(2)
	v_mfma_f32_32x32x16_bf16 v[48:63], v[154:157], v[136:139], v[48:63]
	s_waitcnt lgkmcnt(0)
	v_mfma_f32_32x32x16_bf16 v[48:63], v[164:167], v[140:143], v[48:63]
	ds_read_b64_tr_b16 v[146:147], v144 offset:33856
	ds_read_b64_tr_b16 v[148:149], v144 offset:35968
	ds_read_b64_tr_b16 v[150:151], v144 offset:42304
	ds_read_b64_tr_b16 v[152:153], v144 offset:44416
	ds_read_b64_tr_b16 v[154:155], v144 offset:50752
	ds_read_b64_tr_b16 v[156:157], v144 offset:52864
	ds_read_b64_tr_b16 v[164:165], v144 offset:59200
	ds_read_b64_tr_b16 v[166:167], v144 offset:61312
	v_pk_mul_f32 v[46:47], v[46:47], v[168:169] op_sel_hi:[1,0]
	v_pk_mul_f32 v[44:45], v[44:45], v[168:169] op_sel_hi:[1,0]
	v_pk_mul_f32 v[42:43], v[42:43], v[168:169] op_sel_hi:[1,0]
	v_pk_mul_f32 v[40:41], v[40:41], v[168:169] op_sel_hi:[1,0]
	v_pk_mul_f32 v[38:39], v[38:39], v[168:169] op_sel_hi:[1,0]
	v_pk_mul_f32 v[36:37], v[36:37], v[168:169] op_sel_hi:[1,0]
	v_pk_mul_f32 v[34:35], v[34:35], v[168:169] op_sel_hi:[1,0]
	v_pk_mul_f32 v[32:33], v[32:33], v[168:169] op_sel_hi:[1,0]
	s_waitcnt lgkmcnt(6)
	s_nop 0
	v_mfma_f32_32x32x16_bf16 v[32:47], v[146:149], v[128:131], v[32:47]
	s_waitcnt lgkmcnt(4)
	v_mfma_f32_32x32x16_bf16 v[32:47], v[150:153], v[132:135], v[32:47]
	s_waitcnt lgkmcnt(2)
	v_mfma_f32_32x32x16_bf16 v[32:47], v[154:157], v[136:139], v[32:47]
	s_waitcnt lgkmcnt(0)
	v_mfma_f32_32x32x16_bf16 v[32:47], v[164:167], v[140:143], v[32:47]
	ds_read_b64_tr_b16 v[146:147], v144 offset:33920
	ds_read_b64_tr_b16 v[148:149], v144 offset:36032
	ds_read_b64_tr_b16 v[150:151], v144 offset:42368
	ds_read_b64_tr_b16 v[152:153], v144 offset:44480
	ds_read_b64_tr_b16 v[154:155], v144 offset:50816
	ds_read_b64_tr_b16 v[156:157], v144 offset:52928
	ds_read_b64_tr_b16 v[164:165], v144 offset:59264
	ds_read_b64_tr_b16 v[166:167], v144 offset:61376
	v_pk_mul_f32 v[30:31], v[30:31], v[168:169] op_sel_hi:[1,0]
	v_pk_mul_f32 v[28:29], v[28:29], v[168:169] op_sel_hi:[1,0]
	v_pk_mul_f32 v[26:27], v[26:27], v[168:169] op_sel_hi:[1,0]
	v_pk_mul_f32 v[24:25], v[24:25], v[168:169] op_sel_hi:[1,0]
	v_pk_mul_f32 v[22:23], v[22:23], v[168:169] op_sel_hi:[1,0]
	v_pk_mul_f32 v[20:21], v[20:21], v[168:169] op_sel_hi:[1,0]
	v_pk_mul_f32 v[18:19], v[18:19], v[168:169] op_sel_hi:[1,0]
	v_pk_mul_f32 v[16:17], v[16:17], v[168:169] op_sel_hi:[1,0]
	s_waitcnt lgkmcnt(6)
	s_nop 0
	v_mfma_f32_32x32x16_bf16 v[16:31], v[146:149], v[128:131], v[16:31]
	s_waitcnt lgkmcnt(4)
	v_mfma_f32_32x32x16_bf16 v[16:31], v[150:153], v[132:135], v[16:31]
	s_waitcnt lgkmcnt(2)
	v_mfma_f32_32x32x16_bf16 v[16:31], v[154:157], v[136:139], v[16:31]
	s_waitcnt lgkmcnt(0)
	v_mfma_f32_32x32x16_bf16 v[16:31], v[164:167], v[140:143], v[16:31]
	ds_read_b64_tr_b16 v[146:147], v144 offset:33984
	ds_read_b64_tr_b16 v[148:149], v144 offset:36096
	ds_read_b64_tr_b16 v[150:151], v144 offset:42432
	ds_read_b64_tr_b16 v[152:153], v144 offset:44544
	ds_read_b64_tr_b16 v[154:155], v144 offset:50880
	ds_read_b64_tr_b16 v[156:157], v144 offset:52992
	ds_read_b64_tr_b16 v[164:165], v144 offset:59328
	ds_read_b64_tr_b16 v[166:167], v144 offset:61440
	v_pk_mul_f32 v[14:15], v[14:15], v[168:169] op_sel_hi:[1,0]
	v_pk_mul_f32 v[12:13], v[12:13], v[168:169] op_sel_hi:[1,0]
	v_pk_mul_f32 v[10:11], v[10:11], v[168:169] op_sel_hi:[1,0]
	v_pk_mul_f32 v[8:9], v[8:9], v[168:169] op_sel_hi:[1,0]
	v_pk_mul_f32 v[6:7], v[6:7], v[168:169] op_sel_hi:[1,0]
	v_pk_mul_f32 v[4:5], v[4:5], v[168:169] op_sel_hi:[1,0]
	v_pk_mul_f32 v[2:3], v[2:3], v[168:169] op_sel_hi:[1,0]
	v_pk_mul_f32 v[0:1], v[0:1], v[168:169] op_sel_hi:[1,0]
	s_waitcnt lgkmcnt(6)
	s_nop 0
	v_mfma_f32_32x32x16_bf16 v[0:15], v[146:149], v[128:131], v[0:15]
	s_waitcnt lgkmcnt(4)
	v_mfma_f32_32x32x16_bf16 v[0:15], v[150:153], v[132:135], v[0:15]
	s_waitcnt lgkmcnt(2)
	v_mfma_f32_32x32x16_bf16 v[0:15], v[154:157], v[136:139], v[0:15]
	s_waitcnt lgkmcnt(0)
	v_mfma_f32_32x32x16_bf16 v[0:15], v[164:167], v[140:143], v[0:15]
	ds_read_b64_tr_b16 v[146:147], v144 offset:34048
	ds_read_b64_tr_b16 v[148:149], v144 offset:36160
	ds_read_b64_tr_b16 v[150:151], v144 offset:42496
	ds_read_b64_tr_b16 v[152:153], v144 offset:44608
	ds_read_b64_tr_b16 v[154:155], v144 offset:50944
	ds_read_b64_tr_b16 v[156:157], v144 offset:53056
	ds_read_b64_tr_b16 v[164:165], v144 offset:59392
	ds_read_b64_tr_b16 v[166:167], v144 offset:61504
	v_pk_mul_f32 v[78:79], v[78:79], v[168:169] op_sel_hi:[1,0]
	v_pk_mul_f32 v[76:77], v[76:77], v[168:169] op_sel_hi:[1,0]
	v_pk_mul_f32 v[74:75], v[74:75], v[168:169] op_sel_hi:[1,0]
	v_pk_mul_f32 v[72:73], v[72:73], v[168:169] op_sel_hi:[1,0]
	v_pk_mul_f32 v[70:71], v[70:71], v[168:169] op_sel_hi:[1,0]
	v_pk_mul_f32 v[68:69], v[68:69], v[168:169] op_sel_hi:[1,0]
	v_pk_mul_f32 v[66:67], v[66:67], v[168:169] op_sel_hi:[1,0]
	v_pk_mul_f32 v[64:65], v[64:65], v[168:169] op_sel_hi:[1,0]
	s_waitcnt lgkmcnt(6)
	s_nop 0
	v_mfma_f32_32x32x16_bf16 v[64:79], v[146:149], v[128:131], v[64:79]
	s_waitcnt lgkmcnt(4)
	v_mfma_f32_32x32x16_bf16 v[64:79], v[150:153], v[132:135], v[64:79]
	s_waitcnt lgkmcnt(2)
	v_mfma_f32_32x32x16_bf16 v[64:79], v[154:157], v[136:139], v[64:79]
	s_waitcnt lgkmcnt(0)
; #define LAS __attribute__((address_space(3)))
; DI int opq(int x) { asm volatile("" : "+v"(x)); return x; }
; #define MFMA32(a, b, c) __builtin_amdgcn_mfma_f32_32x32x16_bf16((a), (b), (c), 0, 0, 0)
; DI void phase_mlstm(const Params& p, unsigned char* shm, const int vb) {
;     ...
;                     for (int e = 0; e < 16; ++e) C[ci][e] *= d_last;
;                     __builtin_amdgcn_sched_barrier(0);
; #pragma unroll
;                     for (int kk = 0; kk < 4; ++kk) C[ci] = MFMA32(ka[kk], bw[kk], C[ci]);
;                     __builtin_amdgcn_sched_barrier(0);
;                 }
;             }
;             __syncthreads();
;             {
;                 const int tid = opq(threadIdx.x), r4 = tid >> 5, cgp = tid & 31;
;                 bf16_t* hp = H + (size_t)(t0 + r4) * 2048 + h * 512 + half * 256 + 8 * cgp;
; #pragma unroll
;                 for (int i = 0; i < 4; ++i) *(u32x4*)(hp + (size_t)i * 16 * 2048) = *(const LAS u32x4*)(lds + QI + (r4 + 16 * i) * RS + 16 * cgp);
;             }
	v_mfma_f32_32x32x16_bf16 v[64:79], v[164:167], v[140:143], v[64:79]
	ds_read_b64_tr_b16 v[146:147], v144 offset:34112
	ds_read_b64_tr_b16 v[148:149], v144 offset:36224
	ds_read_b64_tr_b16 v[150:151], v144 offset:42560
	ds_read_b64_tr_b16 v[152:153], v144 offset:44672
	ds_read_b64_tr_b16 v[154:155], v144 offset:51008
	ds_read_b64_tr_b16 v[156:157], v144 offset:53120
	ds_read_b64_tr_b16 v[164:165], v144 offset:59456
	ds_read_b64_tr_b16 v[166:167], v144 offset:61568
	v_pk_mul_f32 v[94:95], v[94:95], v[168:169] op_sel_hi:[1,0]
	v_pk_mul_f32 v[92:93], v[92:93], v[168:169] op_sel_hi:[1,0]
	v_pk_mul_f32 v[90:91], v[90:91], v[168:169] op_sel_hi:[1,0]
	v_pk_mul_f32 v[88:89], v[88:89], v[168:169] op_sel_hi:[1,0]
	v_pk_mul_f32 v[86:87], v[86:87], v[168:169] op_sel_hi:[1,0]
	v_pk_mul_f32 v[84:85], v[84:85], v[168:169] op_sel_hi:[1,0]
	v_pk_mul_f32 v[82:83], v[82:83], v[168:169] op_sel_hi:[1,0]
	v_pk_mul_f32 v[80:81], v[80:81], v[168:169] op_sel_hi:[1,0]
	s_waitcnt lgkmcnt(6)
	s_nop 0
	v_mfma_f32_32x32x16_bf16 v[80:95], v[146:149], v[128:131], v[80:95]
	s_waitcnt lgkmcnt(4)
	v_mfma_f32_32x32x16_bf16 v[80:95], v[150:153], v[132:135], v[80:95]
	s_waitcnt lgkmcnt(2)
	v_mfma_f32_32x32x16_bf16 v[80:95], v[154:157], v[136:139], v[80:95]
	s_waitcnt lgkmcnt(0)
	v_mfma_f32_32x32x16_bf16 v[80:95], v[164:167], v[140:143], v[80:95]
	ds_read_b64_tr_b16 v[146:147], v144 offset:34176
	ds_read_b64_tr_b16 v[148:149], v144 offset:36288
	ds_read_b64_tr_b16 v[150:151], v144 offset:42624
	ds_read_b64_tr_b16 v[152:153], v144 offset:44736
	ds_read_b64_tr_b16 v[154:155], v144 offset:51072
	ds_read_b64_tr_b16 v[156:157], v144 offset:53184
	ds_read_b64_tr_b16 v[164:165], v144 offset:59520
	ds_read_b64_tr_b16 v[166:167], v144 offset:61632
	v_pk_mul_f32 v[110:111], v[110:111], v[168:169] op_sel_hi:[1,0]
	v_pk_mul_f32 v[108:109], v[108:109], v[168:169] op_sel_hi:[1,0]
	v_pk_mul_f32 v[106:107], v[106:107], v[168:169] op_sel_hi:[1,0]
	v_pk_mul_f32 v[104:105], v[104:105], v[168:169] op_sel_hi:[1,0]
	v_pk_mul_f32 v[102:103], v[102:103], v[168:169] op_sel_hi:[1,0]
	v_pk_mul_f32 v[100:101], v[100:101], v[168:169] op_sel_hi:[1,0]
	v_pk_mul_f32 v[98:99], v[98:99], v[168:169] op_sel_hi:[1,0]
	v_pk_mul_f32 v[96:97], v[96:97], v[168:169] op_sel_hi:[1,0]
	s_waitcnt lgkmcnt(6)
	s_nop 0
	v_mfma_f32_32x32x16_bf16 v[96:111], v[146:149], v[128:131], v[96:111]
	s_waitcnt lgkmcnt(4)
	v_mfma_f32_32x32x16_bf16 v[96:111], v[150:153], v[132:135], v[96:111]
	s_waitcnt lgkmcnt(2)
	v_mfma_f32_32x32x16_bf16 v[96:111], v[154:157], v[136:139], v[96:111]
	s_waitcnt lgkmcnt(0)
	v_mfma_f32_32x32x16_bf16 v[96:111], v[164:167], v[140:143], v[96:111]
	ds_read_b64_tr_b16 v[146:147], v144 offset:34240
	ds_read_b64_tr_b16 v[148:149], v144 offset:36352
	ds_read_b64_tr_b16 v[150:151], v144 offset:42688
	ds_read_b64_tr_b16 v[152:153], v144 offset:44800
	ds_read_b64_tr_b16 v[154:155], v144 offset:51136
	ds_read_b64_tr_b16 v[156:157], v144 offset:53248
	ds_read_b64_tr_b16 v[164:165], v144 offset:59584
	ds_read_b64_tr_b16 v[166:167], v144 offset:61696
	v_pk_mul_f32 v[126:127], v[126:127], v[168:169] op_sel_hi:[1,0]
	v_pk_mul_f32 v[124:125], v[124:125], v[168:169] op_sel_hi:[1,0]
	v_pk_mul_f32 v[122:123], v[122:123], v[168:169] op_sel_hi:[1,0]
	v_pk_mul_f32 v[120:121], v[120:121], v[168:169] op_sel_hi:[1,0]
	v_pk_mul_f32 v[118:119], v[118:119], v[168:169] op_sel_hi:[1,0]
	v_pk_mul_f32 v[116:117], v[116:117], v[168:169] op_sel_hi:[1,0]
	v_pk_mul_f32 v[114:115], v[114:115], v[168:169] op_sel_hi:[1,0]
	v_pk_mul_f32 v[112:113], v[112:113], v[168:169] op_sel_hi:[1,0]
	s_waitcnt lgkmcnt(6)
	s_nop 0
	v_mfma_f32_32x32x16_bf16 v[112:127], v[146:149], v[128:131], v[112:127]
	s_waitcnt lgkmcnt(4)
	v_mfma_f32_32x32x16_bf16 v[112:127], v[150:153], v[132:135], v[112:127]
	s_waitcnt lgkmcnt(2)
	v_mfma_f32_32x32x16_bf16 v[112:127], v[154:157], v[136:139], v[112:127]
	s_waitcnt lgkmcnt(0)
	v_mfma_f32_32x32x16_bf16 v[112:127], v[164:167], v[140:143], v[112:127]
	v_mov_b32_e32 v132, v192
	s_barrier
	s_add_u32 s76, s76, 0x100
	v_ashrrev_i32_e32 v128, 5, v132
	v_ashrrev_i32_e32 v129, 31, v128
	v_lshl_add_u64 v[130:131], s[74:75], 0, v[128:129]
	v_lshlrev_b32_e32 v129, 4, v132
	v_lshlrev_b64 v[130:131], 12, v[130:131]
	v_and_b32_e32 v168, 0x1f0, v129
	v_mul_lo_u32 v128, v128, s61
	v_lshl_add_u64 v[130:131], s[70:71], 0, v[130:131]
	v_add3_u32 v136, 0, v168, v128
	v_lshl_add_u64 v[132:133], v[130:131], 0, v[168:169]
	ds_read_b128 v[202:205], v136
	ds_read_b128 v[206:209], v136 offset:8448
	ds_read_b128 v[210:213], v136 offset:16896
	ds_read_b128 v[214:217], v136 offset:25344
	v_add_co_u32_e32 v134, vcc, s97, v132
	s_addc_u32 s77, s77, 0
	s_nop 0
	v_addc_co_u32_e32 v135, vcc, 0, v133, vcc
	v_add_co_u32_e32 v218, vcc, s79, v132
	s_add_u32 s72, s72, 64
	s_addc_u32 s73, s73, 0
	v_addc_co_u32_e32 v219, vcc, 0, v133, vcc
	v_add_co_u32_e32 v220, vcc, s82, v132
	s_add_u32 s74, s74, 64
	s_addc_u32 s75, s75, 0
	v_addc_co_u32_e32 v221, vcc, 0, v133, vcc
	s_waitcnt lgkmcnt(3)
	global_store_dwordx4 v[132:133], v[202:205], off
	s_waitcnt lgkmcnt(2)
	global_store_dwordx4 v[134:135], v[206:209], off
	s_waitcnt lgkmcnt(1)
	global_store_dwordx4 v[218:219], v[210:213], off
	s_waitcnt lgkmcnt(0)
	global_store_dwordx4 v[220:221], v[214:217], off
	s_cmpk_eq_i32 s76, 0x2000
	s_cbranch_scc1 .LBB0_386

; #define LAS __attribute__((address_space(3)))
; DI void phase_rglru(const Params& p, unsigned char* shm) {
;     ...
;             const size_t ob = base + (size_t)tile * 64 * 1536;
; #pragma unroll
;             for (int j = 0; j < 3; ++j) *(u32x4*)(Y + ob + goff[j]) = *(const LAS u32x4*)(lds + GT + loff[j]);
.LBB0_842:
	s_or_b64 exec, exec, s[2:3]
	s_waitcnt lgkmcnt(0)
	s_barrier
	ds_read_b128 v[120:123], v201 offset:52480
	ds_read_b128 v[126:129], v202 offset:52480
	ds_read_b128 v[130:133], v203 offset:52480
	s_lshl_b64 s[2:3], s[10:11], 1
	s_add_u32 s2, s62, s2
	s_addc_u32 s3, s63, s3
	v_lshl_add_u64 v[124:125], v[158:159], 1, s[2:3]
	v_lshl_add_u64 v[134:135], v[160:161], 1, s[2:3]
	v_lshl_add_u64 v[136:137], v[162:163], 1, s[2:3]
	s_add_i32 s64, s64, 1
	s_waitcnt lgkmcnt(2)
	global_store_dwordx4 v[124:125], v[120:123], off
	s_waitcnt lgkmcnt(1)
	global_store_dwordx4 v[134:135], v[126:129], off
	s_waitcnt lgkmcnt(0)
	global_store_dwordx4 v[136:137], v[130:133], off
	s_cmp_eq_u32 s64, 32
	s_cbranch_scc1 .LBB0_816
